# kernel-wide static s_setprio 1 for waves 0-3 (GEMM flips deleted)
# baseline (speedup 1.0000x reference)
; #define LAS __attribute__((address_space(3)))
; __device__ __forceinline__ unsigned xb_add(unsigned* p, unsigned v) { return __hip_atomic_fetch_add(p, v, __ATOMIC_RELAXED, __HIP_MEMORY_SCOPE_AGENT); }
; __device__ __forceinline__ unsigned xb_xcc_id() { return (unsigned)__builtin_amdgcn_s_getreg((3 << 11) | 20) & 0xFu; }
; __device__ __forceinline__ CArgs argp() { CArgs p = (CArgs)__builtin_amdgcn_kernarg_segment_ptr(); asm volatile("" : "+s"(p)); return p; }
; __global__ void __launch_bounds__(NWAVES * 64, 2) mega_fwd(Args a_unused) {
;     extern __shared__ __attribute__((aligned(16))) unsigned char lds_raw[];
;     LAS unsigned char* lds = (LAS unsigned char*)lds_raw;
;     cg::grid_group grid = cg::this_grid();
;     volatile LAS unsigned* bst = (volatile LAS unsigned*)(lds + 131072);
;     if (threadIdx.x < 8) bst[threadIdx.x] = 0u;
;     __syncthreads();
;     if (threadIdx.x == 0) { unsigned* bar_ = (unsigned*)(argp()->ws + WS_BAR); const unsigned x_ = xb_xcc_id(); bst[2] = x_; bst[3] = xb_add(&bar_[XB_XCNT(x_)], 1u); }
_Z8mega_fwd4Args:
	s_load_dwordx2 s[82:83], s[0:1], 0x90
	s_load_dword s72, s[0:1], 0x98
	s_add_u32 s16, s0, 0x90
	v_and_b32_e32 v171, 0x3ff, v0
	s_addc_u32 s17, s1, 0
	v_readfirstlane_b32 s98, v171
	s_nop 3
	s_cmpk_lt_u32 s98, 0x100
	s_cbranch_scc0 .Lk_noprio
	s_setprio 1
.Lk_noprio:
	v_cmp_gt_u32_e32 vcc, 8, v171
	s_and_saveexec_b64 s[4:5], vcc
	v_lshl_add_u32 v1, v171, 2, 0
	v_add_u32_e32 v1, 0x20000, v1
	v_mov_b32_e32 v2, 0
	ds_write_b32 v1, v2
	s_or_b64 exec, exec, s[4:5]
	v_cmp_eq_u32_e64 s[70:71], 0, v171
	s_waitcnt lgkmcnt(0)
	s_barrier
	s_and_saveexec_b64 s[4:5], s[70:71]
	s_cbranch_execz .LBB0_6
	s_mov_b64 s[10:11], s[0:1]
	s_getreg_b32 s3, hwreg(HW_REG_XCC_ID, 0, 4)
	s_and_b32 s3, s3, 15
	s_add_i32 s8, 0, 0x20008
	s_mov_b64 s[6:7], exec
	v_mov_b32_e32 v1, s8
	v_mov_b32_e32 v2, s3
	ds_write_b32 v1, v2
	v_mbcnt_lo_u32_b32 v1, s6, 0
	v_mbcnt_hi_u32_b32 v1, s7, v1
	v_cmp_eq_u32_e32 vcc, 0, v1
	s_and_saveexec_b64 s[8:9], vcc
	s_cbranch_execz .LBB0_5
	s_load_dwordx2 s[10:11], s[10:11], 0x80
	s_lshl_b32 s3, s3, 8
	v_mov_b32_e32 v2, 0x10000
	s_waitcnt lgkmcnt(0)
	s_add_u32 s10, s10, s3
	s_addc_u32 s11, s11, 0
	s_bcnt1_i32_b64 s3, s[6:7]
	v_mov_b32_e32 v3, s3
	global_atomic_add v2, v2, v3, s[10:11] offset:1024 sc0
